# GEMM phases: one static s_setprio 1 for waves 4-7 (the lagging half) for the whole K-loop instead of per-segment flips; reset to 0 at phase end
# speedup vs baseline: 1.0154x; 1.0028x over previous
.LBB0_164:
	s_andn2_b64 vcc, exec, s[4:5]
	s_cbranch_vccnz .LBB0_240
	v_readlane_b32 s10, v255, 40
	v_readlane_b32 s11, v255, 41
	s_load_dwordx2 s[0:1], s[10:11], 0xe0
	v_readlane_b32 s4, v253, 26
	v_mov_b32_e32 v10, v179
	v_readlane_b32 s5, v253, 27
	s_waitcnt lgkmcnt(0)
	s_add_u32 s0, s0, 0x1e34000
	s_addc_u32 s1, s1, 0
	s_andn2_b64 vcc, exec, s[4:5]
	v_readfirstlane_b32 s28, v10
	s_cbranch_vccnz .LBB0_201
	v_lshlrev_b32_e32 v0, 4, v10
	v_add_u32_e32 v1, 0x2000, v0
	v_ashrrev_i32_e32 v2, 31, v1
	v_lshrrev_b32_e32 v2, 22, v2
	v_add_u32_e32 v2, v1, v2
	v_ashrrev_i32_e32 v8, 10, v2
	v_mul_i32_i24_e32 v2, 0x400, v8
	v_sub_u32_e32 v1, v1, v2
	v_lshrrev_b32_e32 v2, 4, v1
	v_bitop3_b32 v1, v2, v1, 32 bitop3:0x6c
	v_readlane_b32 s4, v255, 32
	v_ashrrev_i32_e32 v2, 31, v1
	v_readlane_b32 s5, v255, 33
	v_lshrrev_b32_e32 v2, 26, v2
	s_and_b64 s[4:5], s[4:5], exec
	v_add_u32_e32 v2, v1, v2
	v_lshlrev_b32_e32 v4, 3, v8
	s_cselect_b32 s7, 0x2c00, 0
	v_ashrrev_i32_e32 v3, 6, v2
	v_and_b32_e32 v4, -16, v4
	s_lshl_b32 s4, s7, 12
	v_add_u32_e32 v4, v3, v4
	s_add_u32 s33, s0, s4
	v_and_b32_e32 v3, 3, v3
	s_mov_b32 s4, 0xfffe0
	v_lshrrev_b32_e32 v5, 2, v4
	v_lshlrev_b32_e32 v6, 1, v4
	v_and_or_b32 v3, v4, s4, v3
	v_and_b32_e32 v5, 4, v5
	v_and_b32_e32 v6, 24, v6
	v_and_b32_e32 v2, 0xc0, v2
	v_or3_b32 v3, v3, v5, v6
	v_sub_u32_e32 v1, v1, v2
	v_mov_b32_e32 v6, 1
	v_lshlrev_b32_e32 v5, 5, v8
	v_ashrrev_i16_sdwa v1, v6, sext(v1) dst_sel:DWORD dst_unused:UNUSED_PAD src0_sel:DWORD src1_sel:BYTE_0
	v_lshlrev_b32_e32 v2, 2, v4
	v_and_b32_e32 v5, 32, v5
	v_bfe_i32 v9, v1, 0, 16
	v_and_b32_e32 v11, 0xfffc0, v4
	v_and_b32_e32 v12, 60, v2
	v_bfe_u32 v13, v4, 4, 2
	v_add_lshl_u32 v1, v5, v9, 1
	v_or3_b32 v2, v11, v12, v13
	v_lshl_add_u32 v142, v3, 12, v1
	v_lshl_add_u32 v144, v2, 12, v1
	v_bfe_i32 v1, v10, 27, 1
	v_lshrrev_b32_e32 v1, 22, v1
	v_add_u32_e32 v1, v0, v1
	v_and_b32_e32 v1, 0xfffffc00, v1
	v_sub_u32_e32 v0, v0, v1
	v_ashrrev_i32_e32 v2, 31, v10
	v_lshrrev_b32_e32 v1, 4, v0
	v_lshrrev_b32_e32 v2, 26, v2
	v_bitop3_b32 v1, v1, v0, 32 bitop3:0x6c
	v_ashrrev_i32_e32 v0, 31, v0
	v_add_u32_e32 v2, v10, v2
	v_lshrrev_b32_e32 v0, 26, v0
	v_ashrrev_i32_e32 v14, 6, v2
	v_add_u32_e32 v0, v1, v0
	v_lshlrev_b32_e32 v2, 3, v14
	v_ashrrev_i32_e32 v0, 6, v0
	v_and_b32_e32 v2, -16, v2
	v_add_u32_e32 v2, v0, v2
	v_and_b32_e32 v3, 3, v0
	v_lshrrev_b32_e32 v4, 2, v2
	v_lshlrev_b32_e32 v5, 1, v2
	v_mul_i32_i24_e32 v0, 64, v0
	s_addc_u32 s37, s1, 0
	s_ashr_i32 s6, s28, 6
	v_and_or_b32 v3, v2, s4, v3
	v_and_b32_e32 v4, 4, v4
	v_and_b32_e32 v5, 24, v5
	v_sub_u32_e32 v0, v1, v0
	s_ashr_i32 s38, s28, 8
	s_lshl_b32 s39, s6, 10
	v_or3_b32 v3, v3, v4, v5
	v_lshlrev_b32_e32 v4, 5, v14
	v_ashrrev_i16_sdwa v0, v6, sext(v0) dst_sel:DWORD dst_unused:UNUSED_PAD src0_sel:DWORD src1_sel:BYTE_0
	v_readlane_b32 s4, v254, 3
	v_and_b32_e32 v4, 32, v4
	v_bfe_i32 v15, v0, 0, 16
	v_readlane_b32 s5, v254, 4
	s_add_u32 s64, s33, s4
	v_add_lshl_u32 v0, v4, v15, 1
	s_addc_u32 s65, s37, s5
	s_add_i32 s44, s39, 0
	v_lshl_add_u32 v146, v3, 12, v0
	v_lshlrev_b32_e32 v1, 2, v2
	s_add_i32 m0, s44, 0x10000
	v_and_b32_e32 v16, 0xfffc0, v2
	v_and_b32_e32 v17, 60, v1
	v_bfe_u32 v18, v2, 4, 2
	global_load_lds_dwordx4 v146, s[64:65]
	s_add_i32 m0, s44, 0x12000
	v_readlane_b32 s4, v254, 11
	v_readlane_b32 s8, v255, 26
	v_or3_b32 v1, v16, v17, v18
	v_readlane_b32 s5, v254, 12
	v_readlane_b32 s9, v255, 27
	s_add_u32 s62, s8, s4
	v_lshl_add_u32 v148, v1, 12, v0
	global_load_lds_dwordx4 v142, s[64:65]
	s_addc_u32 s63, s9, s5
	s_mov_b32 m0, s44
	s_add_i32 s72, s44, 0x2000
	global_load_lds_dwordx4 v148, s[62:63]
	s_mov_b32 m0, s72
	s_add_u32 s4, s64, 0x80000
	global_load_lds_dwordx4 v144, s[62:63]
	s_addc_u32 s5, s65, 0
	s_add_i32 m0, s44, 0x14000
	v_mov_b32_e32 v147, v177
	global_load_lds_dwordx4 v146, s[4:5]
	s_add_i32 m0, s44, 0x16000
	v_mov_b32_e32 v143, v177
	global_load_lds_dwordx4 v142, s[4:5]
	s_add_u32 s4, s62, 0x80000
	s_addc_u32 s5, s63, 0
	s_add_i32 s73, s44, 0x4000
	s_mov_b32 m0, s73
	s_add_i32 s74, s44, 0x6000
	global_load_lds_dwordx4 v148, s[4:5]
	s_mov_b32 m0, s74
	v_mov_b32_e32 v149, v177
	global_load_lds_dwordx4 v144, s[4:5]
	v_mov_b32_e32 v145, v177
	v_mov_b32_e32 v202, 0x1f8
	v_lshl_add_u64 v[6:7], s[64:65], 0, v[146:147]
	v_lshl_add_u64 v[4:5], s[64:65], 0, v[142:143]
	v_lshl_add_u64 v[2:3], s[62:63], 0, v[148:149]
	s_cmp_lg_u32 s38, 1
	v_lshl_add_u64 v[0:1], s[62:63], 0, v[144:145]
	s_cbranch_scc1 .LBB0_168
	s_barrier
	s_setprio 1

.LBB0_198:
	s_waitcnt vmcnt(0)
	s_setprio 0
	s_cmpk_gt_u32 s28, 0xff
	s_cbranch_scc1 .LBB0_200
	s_barrier

.LBB0_252:
	v_readlane_b32 s0, v253, 42
	v_mov_b32_e32 v18, v179
	v_readlane_b32 s1, v253, 43
	s_andn2_b64 vcc, exec, s[0:1]
	v_readfirstlane_b32 s0, v18
	s_cbranch_vccnz .LBB0_332
	v_lshlrev_b32_e32 v0, 4, v18
	v_add_u32_e32 v1, 0x2000, v0
	v_ashrrev_i32_e32 v2, 31, v1
	v_lshrrev_b32_e32 v2, 22, v2
	v_add_u32_e32 v2, v1, v2
	v_ashrrev_i32_e32 v2, 10, v2
	v_mul_i32_i24_e32 v3, 0x400, v2
	v_sub_u32_e32 v1, v1, v3
	v_lshrrev_b32_e32 v3, 4, v1
	s_load_dwordx2 s[12:13], s[12:13], 0xe0
	v_bitop3_b32 v1, v3, v1, 32 bitop3:0x6c
	v_ashrrev_i32_e32 v3, 31, v1
	v_lshrrev_b32_e32 v3, 26, v3
	v_add_u32_e32 v3, v1, v3
	v_lshlrev_b32_e32 v5, 3, v2
	v_ashrrev_i32_e32 v4, 6, v3
	v_and_b32_e32 v5, -16, v5
	s_waitcnt lgkmcnt(0)
	s_add_u32 s1, s12, s8
	v_add_u32_e32 v5, v4, v5
	s_addc_u32 s28, s13, s9
	v_and_b32_e32 v4, 3, v4
	s_mov_b32 s9, 0x7fffffe0
	v_lshrrev_b32_e32 v6, 2, v5
	v_lshlrev_b32_e32 v7, 1, v5
	v_lshlrev_b32_e32 v2, 5, v2
	v_and_or_b32 v4, v5, s9, v4
	v_and_b32_e32 v6, 4, v6
	v_and_b32_e32 v7, 24, v7
	v_and_b32_e32 v12, 32, v2
	v_and_b32_e32 v2, 0xc0, v3
	v_or3_b32 v4, v4, v6, v7
	v_sub_u32_e32 v1, v1, v2
	v_mov_b32_e32 v7, 1
	v_ashrrev_i16_sdwa v1, v7, sext(v1) dst_sel:DWORD dst_unused:UNUSED_PAD src0_sel:DWORD src1_sel:BYTE_0
	v_bfe_i32 v13, v1, 0, 16
	v_mul_lo_u32 v4, v4, s10
	v_add_u32_e32 v1, v12, v13
	v_mul_lo_u32 v14, v5, s10
	v_add_lshl_u32 v168, v4, v1, 1
	v_add_lshl_u32 v170, v1, v14, 1
	v_bfe_i32 v1, v18, 27, 1
	v_lshrrev_b32_e32 v1, 22, v1
	v_add_u32_e32 v1, v0, v1
	v_and_b32_e32 v1, 0xfffffc00, v1
	v_sub_u32_e32 v0, v0, v1
	v_ashrrev_i32_e32 v2, 31, v18
	v_lshrrev_b32_e32 v1, 4, v0
	v_lshrrev_b32_e32 v2, 26, v2
	v_bitop3_b32 v1, v1, v0, 32 bitop3:0x6c
	v_ashrrev_i32_e32 v0, 31, v0
	v_add_u32_e32 v2, v18, v2
	v_lshrrev_b32_e32 v0, 26, v0
	v_ashrrev_i32_e32 v2, 6, v2
	v_add_u32_e32 v0, v1, v0
	v_lshlrev_b32_e32 v3, 3, v2
	v_ashrrev_i32_e32 v0, 6, v0
	v_and_b32_e32 v3, -16, v3
	v_add_u32_e32 v3, v0, v3
	v_and_b32_e32 v4, 3, v0
	v_mul_i32_i24_e32 v0, 64, v0
	v_readlane_b32 s12, v254, 5
	s_ashr_i32 s7, s0, 6
	s_lshl_b32 s30, s10, 9
	v_lshrrev_b32_e32 v5, 2, v3
	v_lshlrev_b32_e32 v6, 1, v3
	v_sub_u32_e32 v0, v1, v0
	v_readlane_b32 s13, v254, 6
	s_mov_b32 s20, s12
	s_ashr_i32 s8, s0, 8
	s_lshl_b32 s44, s10, 8
	s_lshl_b32 s31, s7, 10
	v_and_or_b32 v4, v3, s9, v4
	v_and_b32_e32 v5, 4, v5
	v_and_b32_e32 v6, 24, v6
	v_lshlrev_b32_e32 v2, 5, v2
	v_ashrrev_i16_sdwa v0, v7, sext(v0) dst_sel:DWORD dst_unused:UNUSED_PAD src0_sel:DWORD src1_sel:BYTE_0
	s_mul_i32 s13, s30, s20
	v_or3_b32 v4, v4, v5, v6
	v_and_b32_e32 v15, 32, v2
	v_bfe_i32 v16, v0, 0, 16
	s_mul_hi_i32 s12, s30, s12
	s_add_u32 s24, s1, s13
	v_mul_lo_u32 v4, v4, s10
	v_add_u32_e32 v0, v15, v16
	s_addc_u32 s25, s28, s12
	s_add_i32 s33, s31, 0
	v_add_lshl_u32 v176, v4, v0, 1
	v_readlane_b32 s11, v253, 60
	s_add_i32 m0, s33, 0x10000
	s_mul_hi_i32 s9, s30, s11
	s_mul_i32 s11, s30, s11
	global_load_lds_dwordx4 v176, s[24:25]
	s_add_i32 m0, s33, 0x12000
	v_mul_lo_u32 v17, v3, s10
	s_add_u32 s26, s2, s11
	v_add_lshl_u32 v172, v0, v17, 1
	global_load_lds_dwordx4 v168, s[24:25]
	s_addc_u32 s27, s3, s9
	s_mov_b32 m0, s33
	s_add_i32 s37, s33, 0x2000
	global_load_lds_dwordx4 v172, s[26:27]
	s_mov_b32 m0, s37
	s_add_u32 s12, s24, s44
	global_load_lds_dwordx4 v170, s[26:27]
	s_addc_u32 s13, s25, 0
	s_add_i32 m0, s33, 0x14000
	v_mov_b32_e32 v169, v177
	global_load_lds_dwordx4 v176, s[12:13]
	s_add_i32 m0, s33, 0x16000
	v_lshl_add_u64 v[8:9], s[12:13], 0, v[176:177]
	v_lshl_add_u64 v[10:11], s[12:13], 0, v[168:169]
	global_load_lds_dwordx4 v168, s[12:13]
	s_add_u32 s12, s26, s44
	s_addc_u32 s13, s27, 0
	s_add_i32 s38, s33, 0x4000
	s_mov_b32 m0, s38
	s_add_i32 s39, s33, 0x6000
	global_load_lds_dwordx4 v172, s[12:13]
	s_mov_b32 m0, s39
	v_mov_b32_e32 v173, v177
	global_load_lds_dwordx4 v170, s[12:13]
	v_mov_b32_e32 v171, v177
	v_lshl_add_u64 v[0:1], s[24:25], 0, v[176:177]
	v_lshl_add_u64 v[2:3], s[24:25], 0, v[168:169]
	v_lshl_add_u64 v[4:5], s[26:27], 0, v[172:173]
	v_lshl_add_u64 v[6:7], s[26:27], 0, v[170:171]
	s_cmp_lg_u32 s8, 1
	s_cbranch_scc1 .LBB0_255
	s_barrier
	s_setprio 1

.LBB0_329:
	s_waitcnt vmcnt(0)
	s_setprio 0
	s_cmpk_gt_u32 s0, 0xff
	s_cbranch_scc1 .LBB0_331
	s_barrier

.LBB0_633:
	s_load_dwordx2 s[10:11], s[10:11], 0xe0
	v_bfe_i32 v2, v12, 27, 1
	v_lshlrev_b32_e32 v0, 4, v12
	v_lshrrev_b32_e32 v2, 22, v2
	v_add_u32_e32 v2, v0, v2
	s_and_b64 s[6:7], s[2:3], exec
	s_mov_b32 s5, 0x9034000
	v_and_b32_e32 v2, 0xfffffc00, v2
	s_cselect_b32 s5, s5, 0xa034000
	v_sub_u32_e32 v2, v0, v2
	s_waitcnt lgkmcnt(0)
	s_add_u32 s37, s10, s5
	v_lshrrev_b32_e32 v3, 4, v2
	s_addc_u32 s38, s11, 0
	v_ashrrev_i32_e32 v1, 31, v12
	v_bitop3_b32 v3, v3, v2, 32 bitop3:0x6c
	v_ashrrev_i32_e32 v2, 31, v2
	s_and_b64 s[6:7], s[2:3], exec
	s_mov_b32 s5, 0xac74000
	v_lshrrev_b32_e32 v1, 26, v1
	v_lshrrev_b32_e32 v2, 26, v2
	s_cselect_b32 s5, s5, 0xcc74000
	v_add_u32_e32 v1, v12, v1
	v_add_u32_e32 v2, v3, v2
	s_add_u32 s39, s10, s5
	v_ashrrev_i32_e32 v1, 6, v1
	v_ashrrev_i32_e32 v2, 6, v2
	s_addc_u32 s46, s11, 0
	v_lshlrev_b32_e32 v4, 3, v1
	v_mul_i32_i24_e32 v5, 64, v2
	s_and_b64 s[6:7], s[2:3], exec
	s_movk_i32 s5, 0x200
	v_and_b32_e32 v4, -16, v4
	v_lshlrev_b32_e32 v1, 5, v1
	v_sub_u32_e32 v3, v3, v5
	v_mov_b32_e32 v6, 1
	s_cselect_b32 s47, 0x80, s5
	s_movk_i32 s5, 0x1000
	v_add_u32_e32 v4, v2, v4
	v_and_b32_e32 v1, 32, v1
	v_ashrrev_i16_sdwa v3, v6, sext(v3) dst_sel:DWORD dst_unused:UNUSED_PAD src0_sel:DWORD src1_sel:BYTE_0
	s_cselect_b32 s6, s5, 0x200
	s_ashr_i32 s5, s1, 6
	v_add_u32_sdwa v1, v1, sext(v3) dst_sel:DWORD dst_unused:UNUSED_PAD src0_sel:DWORD src1_sel:WORD_0
	v_lshlrev_b32_e32 v3, 1, v4
	v_lshrrev_b32_e32 v5, 2, v4
	v_and_b32_e32 v2, 3, v2
	s_mov_b32 s9, 0x7fffffe0
	v_and_b32_e32 v3, 24, v3
	v_and_b32_e32 v5, 4, v5
	v_and_or_b32 v2, v4, s9, v2
	s_and_b64 s[10:11], s[2:3], exec
	v_or3_b32 v2, v2, v5, v3
	s_cselect_b32 s7, 12, 9
	v_lshlrev_b32_e32 v3, s7, v4
	v_lshlrev_b32_e32 v2, s7, v2
	v_add_u32_e32 v0, 0x2000, v0
	v_add_lshl_u32 v128, v1, v3, 1
	v_add_lshl_u32 v130, v2, v1, 1
	v_ashrrev_i32_e32 v1, 31, v0
	v_lshrrev_b32_e32 v1, 22, v1
	v_add_u32_e32 v1, v0, v1
	v_ashrrev_i32_e32 v1, 10, v1
	v_mul_i32_i24_e32 v2, 0x400, v1
	v_sub_u32_e32 v0, v0, v2
	v_lshrrev_b32_e32 v2, 4, v0
	v_bitop3_b32 v0, v2, v0, 32 bitop3:0x6c
	v_ashrrev_i32_e32 v3, 31, v0
	v_lshrrev_b32_e32 v3, 26, v3
	v_add_u32_e32 v3, v0, v3
	v_lshlrev_b32_e32 v2, 3, v1
	v_ashrrev_i32_e32 v4, 6, v3
	v_and_b32_e32 v3, 0xc0, v3
	v_and_b32_e32 v2, -16, v2
	v_lshlrev_b32_e32 v1, 5, v1
	v_sub_u32_e32 v0, v0, v3
	v_add_u32_e32 v2, v4, v2
	v_and_b32_e32 v1, 32, v1
	v_ashrrev_i16_sdwa v0, v6, sext(v0) dst_sel:DWORD dst_unused:UNUSED_PAD src0_sel:DWORD src1_sel:BYTE_0
	v_add_u32_sdwa v0, v1, sext(v0) dst_sel:DWORD dst_unused:UNUSED_PAD src0_sel:DWORD src1_sel:WORD_0
	v_lshlrev_b32_e32 v1, 1, v2
	v_lshrrev_b32_e32 v3, 2, v2
	v_and_b32_e32 v4, 3, v4
	v_and_b32_e32 v1, 24, v1
	v_and_b32_e32 v3, 4, v3
	v_and_or_b32 v4, v2, s9, v4
	v_or3_b32 v1, v4, v3, v1
	v_lshlrev_b32_e32 v2, s7, v2
	v_lshlrev_b32_e32 v1, s7, v1
	v_add_lshl_u32 v132, v0, v2, 1
	v_add_lshl_u32 v134, v1, v0, 1
	v_cvt_f32_u32_e32 v0, s47
	s_sub_i32 s11, 0, s47
	v_readlane_b32 s9, v254, 15
	s_add_i32 s8, s8, s9
	v_rcp_iflag_f32_e32 v0, v0
	s_abs_i32 s10, s8
	s_ashr_i32 s7, s1, 8
	s_lshl_b32 s44, s6, 8
	v_mul_f32_e32 v0, 0x4f7ffffe, v0
	v_cvt_u32_f32_e32 v0, v0
	s_lshl_b32 s48, s5, 10
	s_ashr_i32 s9, s8, 31
	v_mov_b32_e32 v131, v177
	v_readfirstlane_b32 s49, v0
	s_mul_i32 s11, s11, s49
	s_mul_hi_u32 s11, s49, s11
	s_add_i32 s49, s49, s11
	s_mul_hi_u32 s11, s10, s49
	s_mul_i32 s12, s11, s47
	s_sub_i32 s10, s10, s12
	s_add_i32 s12, s11, 1
	s_sub_i32 s13, s10, s47
	s_cmp_ge_u32 s10, s47
	s_cselect_b32 s11, s12, s11
	s_cselect_b32 s10, s13, s10
	s_add_i32 s12, s11, 1
	s_cmp_ge_u32 s10, s47
	s_cselect_b32 s10, s12, s11
	s_xor_b32 s10, s10, s9
	s_sub_i32 s9, s10, s9
	s_lshl_b32 s10, s9, 3
	s_sub_i32 s11, s0, s10
	s_min_i32 s11, s11, 8
	s_mul_i32 s9, s9, s47
	s_sub_i32 s12, s8, s9
	s_sext_i32_i16 s9, s11
	v_cvt_f32_i32_e32 v1, s9
	s_sext_i32_i16 s8, s12
	v_cvt_f32_i32_e32 v0, s8
	s_xor_b32 s13, s8, s9
	v_rcp_iflag_f32_e32 v2, v1
	s_ashr_i32 s13, s13, 30
	s_or_b32 s13, s13, 1
	v_mov_b32_e32 v135, v177
	v_mul_f32_e32 v2, v0, v2
	v_trunc_f32_e32 v2, v2
	v_fma_f32 v0, -v2, v1, v0
	v_cvt_i32_f32_e32 v2, v2
	v_cmp_ge_f32_e64 s[8:9], |v0|, |v1|
	s_and_b64 s[8:9], s[8:9], exec
	s_cselect_b32 s8, s13, 0
	v_readfirstlane_b32 s9, v2
	s_add_i32 s8, s9, s8
	s_sext_i32_i16 s16, s8
	s_mul_i32 s8, s8, s11
	s_sub_i32 s8, s12, s8
	s_sext_i32_i16 s8, s8
	s_add_i32 s18, s10, s8
	s_ashr_i32 s19, s18, 31
	s_and_b64 s[8:9], s[2:3], exec
	s_cselect_b32 s50, 21, 18
	s_ashr_i32 s17, s16, 31
	s_lshl_b64 s[8:9], s[18:19], s50
	s_lshl_b64 s[10:11], s[16:17], s50
	s_add_u32 s30, s39, s10
	s_addc_u32 s31, s46, s11
	s_add_i32 s17, s48, 0
	s_add_i32 m0, s17, 0x10000
	v_mov_b32_e32 v129, v177
	global_load_lds_dwordx4 v130, s[30:31]
	s_add_i32 m0, s17, 0x12000
	s_add_u32 s26, s37, s8
	global_load_lds_dwordx4 v134, s[30:31]
	s_addc_u32 s27, s38, s9
	s_mov_b32 m0, s17
	s_add_i32 s19, s17, 0x2000
	global_load_lds_dwordx4 v128, s[26:27]
	s_mov_b32 m0, s19
	s_add_u32 s8, s30, s44
	global_load_lds_dwordx4 v132, s[26:27]
	s_addc_u32 s9, s31, 0
	s_add_i32 m0, s17, 0x14000
	v_lshl_add_u64 v[8:9], s[8:9], 0, v[130:131]
	global_load_lds_dwordx4 v130, s[8:9]
	s_add_i32 m0, s17, 0x16000
	v_lshl_add_u64 v[10:11], s[8:9], 0, v[134:135]
	global_load_lds_dwordx4 v134, s[8:9]
	s_add_u32 s8, s26, s44
	s_addc_u32 s9, s27, 0
	s_add_i32 s51, s17, 0x4000
	s_mov_b32 m0, s51
	s_add_i32 s52, s17, 0x6000
	global_load_lds_dwordx4 v128, s[8:9]
	s_mov_b32 m0, s52
	v_mov_b32_e32 v133, v177
	global_load_lds_dwordx4 v132, s[8:9]
	v_lshl_add_u64 v[0:1], s[30:31], 0, v[130:131]
	v_lshl_add_u64 v[2:3], s[30:31], 0, v[134:135]
	v_lshl_add_u64 v[4:5], s[26:27], 0, v[128:129]
	v_lshl_add_u64 v[6:7], s[26:27], 0, v[132:133]
	s_cmp_lg_u32 s7, 1
	s_cbranch_scc1 .LBB0_635
	s_barrier
	s_setprio 1

.LBB0_639:
	s_add_i32 s60, s30, 2
	s_add_u32 s29, s26, 0x80
	s_addc_u32 s31, s27, 0
	s_add_i32 s34, 0, 0x10000
	v_add_u32_e32 v156, s34, v141
	ds_read_b128 v[144:147], v156
	ds_read_b128 v[148:151], v156 offset:1024
	ds_read_b128 v[152:155], v156 offset:2048
	ds_read_b128 v[156:159], v156 offset:3072
	s_cmp_eq_u32 s58, s30
	s_cselect_b32 s30, s20, s29
	s_cselect_b32 s31, s21, s31
	s_cselect_b32 s43, s25, s15
	s_cselect_b32 s42, s24, s13
	v_lshl_add_u64 v[196:197], s[26:27], 0, v[136:137]
	s_add_i32 m0, s17, 0xc000
	ds_read_b128 v[160:163], v143
	ds_read_b128 v[164:167], v143 offset:1024
	ds_read_b128 v[168:171], v143 offset:2048
	ds_read_b128 v[172:175], v143 offset:3072
	ds_read_b128 v[180:183], v143 offset:4096
	ds_read_b128 v[184:187], v143 offset:5120
	ds_read_b128 v[188:191], v143 offset:6144
	ds_read_b128 v[192:195], v143 offset:7168
	global_load_lds_dwordx4 v[196:197], off
	v_lshl_add_u64 v[196:197], s[26:27], 0, v[138:139]
	s_add_i32 m0, s17, 0xe000
	s_nop 0
	global_load_lds_dwordx4 v[196:197], off
	s_waitcnt lgkmcnt(8)
	s_barrier
	s_waitcnt lgkmcnt(0)
	s_waitcnt lgkmcnt(0)
	v_mfma_f32_16x16x32_bf16 v[124:127], v[144:147], v[160:163], v[124:127]
	v_mfma_f32_16x16x32_bf16 v[120:123], v[152:155], v[160:163], v[120:123]
	v_mfma_f32_16x16x32_bf16 v[116:119], v[144:147], v[168:171], v[116:119]
	v_mfma_f32_16x16x32_bf16 v[112:115], v[152:155], v[168:171], v[112:115]
	v_mfma_f32_16x16x32_bf16 v[108:111], v[144:147], v[180:183], v[108:111]
	v_mfma_f32_16x16x32_bf16 v[104:107], v[152:155], v[180:183], v[104:107]
	v_mfma_f32_16x16x32_bf16 v[100:103], v[144:147], v[188:191], v[100:103]
	v_mfma_f32_16x16x32_bf16 v[96:99], v[152:155], v[188:191], v[96:99]
	v_mfma_f32_16x16x32_bf16 v[124:127], v[148:151], v[164:167], v[124:127]
	v_mfma_f32_16x16x32_bf16 v[120:123], v[156:159], v[164:167], v[120:123]
	v_mfma_f32_16x16x32_bf16 v[116:119], v[148:151], v[172:175], v[116:119]
	v_mfma_f32_16x16x32_bf16 v[112:115], v[156:159], v[172:175], v[112:115]
	v_mfma_f32_16x16x32_bf16 v[108:111], v[148:151], v[184:187], v[108:111]
	v_mfma_f32_16x16x32_bf16 v[104:107], v[156:159], v[184:187], v[104:107]
	v_mfma_f32_16x16x32_bf16 v[100:103], v[148:151], v[192:195], v[100:103]
	v_mfma_f32_16x16x32_bf16 v[96:99], v[156:159], v[192:195], v[96:99]
	s_barrier
	s_add_i32 s29, 0, 0x14000
	s_add_i32 s34, s34, s48
	v_add_u32_e32 v176, s29, v141
	v_lshl_add_u64 v[200:201], s[42:43], 0, v[130:131]
	s_mov_b32 m0, s34
	ds_read_b128 v[196:199], v176
	ds_read_b128 v[208:211], v176 offset:1024
	ds_read_b128 v[212:215], v176 offset:2048
	ds_read_b128 v[216:219], v176 offset:3072
	global_load_lds_dwordx4 v[200:201], off
	v_lshl_add_u64 v[220:221], s[42:43], 0, v[134:135]
	s_add_i32 m0, s34, 0x2000
	s_nop 0
	global_load_lds_dwordx4 v[220:221], off
	s_barrier
	s_waitcnt lgkmcnt(0)
	s_waitcnt lgkmcnt(0)
	v_mfma_f32_16x16x32_bf16 v[72:75], v[196:199], v[160:163], v[72:75]
	v_mfma_f32_16x16x32_bf16 v[64:67], v[212:215], v[160:163], v[64:67]
	v_mfma_f32_16x16x32_bf16 v[56:59], v[196:199], v[168:171], v[56:59]
	v_mfma_f32_16x16x32_bf16 v[48:51], v[212:215], v[168:171], v[48:51]
	v_mfma_f32_16x16x32_bf16 v[44:47], v[196:199], v[180:183], v[44:47]
	v_mfma_f32_16x16x32_bf16 v[40:43], v[212:215], v[180:183], v[40:43]
	v_mfma_f32_16x16x32_bf16 v[36:39], v[196:199], v[188:191], v[36:39]
	v_mfma_f32_16x16x32_bf16 v[32:35], v[212:215], v[188:191], v[32:35]
	v_mfma_f32_16x16x32_bf16 v[72:75], v[208:211], v[164:167], v[72:75]
	v_mfma_f32_16x16x32_bf16 v[64:67], v[216:219], v[164:167], v[64:67]
	v_mfma_f32_16x16x32_bf16 v[56:59], v[208:211], v[172:175], v[56:59]
	v_mfma_f32_16x16x32_bf16 v[48:51], v[216:219], v[172:175], v[48:51]
	v_mfma_f32_16x16x32_bf16 v[44:47], v[208:211], v[184:187], v[44:47]
	v_mfma_f32_16x16x32_bf16 v[40:43], v[216:219], v[184:187], v[40:43]
	v_mfma_f32_16x16x32_bf16 v[36:39], v[208:211], v[192:195], v[36:39]
	v_mfma_f32_16x16x32_bf16 v[32:35], v[216:219], v[192:195], v[32:35]
	s_mov_b32 m0, s17
	v_lshl_add_u64 v[222:223], s[30:31], 0, v[128:129]
	s_barrier
	ds_read_b128 v[160:163], v143 offset:16384
	ds_read_b128 v[164:167], v143 offset:17408
	ds_read_b128 v[168:171], v143 offset:18432
	ds_read_b128 v[172:175], v143 offset:19456
	ds_read_b128 v[180:183], v143 offset:20480
	ds_read_b128 v[184:187], v143 offset:21504
	ds_read_b128 v[188:191], v143 offset:22528
	ds_read_b128 v[192:195], v143 offset:23552
	global_load_lds_dwordx4 v[222:223], off
	v_lshl_add_u64 v[224:225], s[30:31], 0, v[132:133]
	s_mov_b32 m0, s19
	s_nop 0
	global_load_lds_dwordx4 v[224:225], off
	s_barrier
	s_waitcnt lgkmcnt(0)
	s_waitcnt lgkmcnt(0)
	v_mfma_f32_16x16x32_bf16 v[92:95], v[144:147], v[160:163], v[92:95]
	v_mfma_f32_16x16x32_bf16 v[88:91], v[152:155], v[160:163], v[88:91]
	v_mfma_f32_16x16x32_bf16 v[84:87], v[144:147], v[168:171], v[84:87]
	v_mfma_f32_16x16x32_bf16 v[80:83], v[152:155], v[168:171], v[80:83]
	v_mfma_f32_16x16x32_bf16 v[76:79], v[144:147], v[180:183], v[76:79]
	v_mfma_f32_16x16x32_bf16 v[68:71], v[152:155], v[180:183], v[68:71]
	v_mfma_f32_16x16x32_bf16 v[60:63], v[144:147], v[188:191], v[60:63]
	v_mfma_f32_16x16x32_bf16 v[52:55], v[152:155], v[188:191], v[52:55]
	v_mfma_f32_16x16x32_bf16 v[92:95], v[148:151], v[164:167], v[92:95]
	v_mfma_f32_16x16x32_bf16 v[88:91], v[156:159], v[164:167], v[88:91]
	v_mfma_f32_16x16x32_bf16 v[84:87], v[148:151], v[172:175], v[84:87]
	v_mfma_f32_16x16x32_bf16 v[80:83], v[156:159], v[172:175], v[80:83]
	v_mfma_f32_16x16x32_bf16 v[76:79], v[148:151], v[184:187], v[76:79]
	v_mfma_f32_16x16x32_bf16 v[68:71], v[156:159], v[184:187], v[68:71]
	v_mfma_f32_16x16x32_bf16 v[60:63], v[148:151], v[192:195], v[60:63]
	v_mfma_f32_16x16x32_bf16 v[52:55], v[156:159], v[192:195], v[52:55]
	s_barrier
	s_add_u32 s34, s42, s44
	s_addc_u32 s35, s43, 0
	s_add_i32 s29, s29, s48
	v_lshl_add_u64 v[226:227], s[34:35], 0, v[130:131]
	s_mov_b32 m0, s29
	v_lshl_add_u64 v[228:229], s[34:35], 0, v[134:135]
	global_load_lds_dwordx4 v[226:227], off
	s_add_i32 m0, s29, 0x2000
	s_nop 0
	global_load_lds_dwordx4 v[228:229], off
	s_waitcnt vmcnt(6)
	s_barrier
	v_mfma_f32_16x16x32_bf16 v[28:31], v[196:199], v[160:163], v[28:31]
	v_mfma_f32_16x16x32_bf16 v[24:27], v[212:215], v[160:163], v[24:27]
	v_mfma_f32_16x16x32_bf16 v[20:23], v[196:199], v[168:171], v[20:23]
	v_mfma_f32_16x16x32_bf16 v[16:19], v[212:215], v[168:171], v[16:19]
	v_mfma_f32_16x16x32_bf16 v[12:15], v[196:199], v[180:183], v[12:15]
	v_mfma_f32_16x16x32_bf16 v[8:11], v[212:215], v[180:183], v[8:11]
	v_mfma_f32_16x16x32_bf16 v[4:7], v[196:199], v[188:191], v[4:7]
	v_mfma_f32_16x16x32_bf16 v[0:3], v[212:215], v[188:191], v[0:3]
	v_mfma_f32_16x16x32_bf16 v[28:31], v[208:211], v[164:167], v[28:31]
	v_mfma_f32_16x16x32_bf16 v[24:27], v[216:219], v[164:167], v[24:27]
	v_mfma_f32_16x16x32_bf16 v[20:23], v[208:211], v[172:175], v[20:23]
	v_mfma_f32_16x16x32_bf16 v[16:19], v[216:219], v[172:175], v[16:19]
	v_mfma_f32_16x16x32_bf16 v[12:15], v[208:211], v[184:187], v[12:15]
	v_mfma_f32_16x16x32_bf16 v[8:11], v[216:219], v[184:187], v[8:11]
	v_mfma_f32_16x16x32_bf16 v[4:7], v[208:211], v[192:195], v[4:7]
	v_mfma_f32_16x16x32_bf16 v[0:3], v[216:219], v[192:195], v[0:3]
	s_add_i32 s29, 0, 0x18000
	v_add_u32_e32 v156, s29, v141
	s_barrier
	ds_read_b128 v[144:147], v156
	ds_read_b128 v[148:151], v156 offset:1024
	ds_read_b128 v[152:155], v156 offset:2048
	ds_read_b128 v[156:159], v156 offset:3072
	s_add_u32 s30, s30, s44
	s_addc_u32 s31, s31, 0
	s_mov_b32 m0, s51
	v_lshl_add_u64 v[196:197], s[30:31], 0, v[128:129]
	ds_read_b128 v[160:163], v143 offset:32768
	ds_read_b128 v[164:167], v143 offset:33792
	ds_read_b128 v[168:171], v143 offset:34816
	ds_read_b128 v[172:175], v143 offset:35840
	ds_read_b128 v[180:183], v143 offset:36864
	ds_read_b128 v[184:187], v143 offset:37888
	ds_read_b128 v[188:191], v143 offset:38912
	ds_read_b128 v[192:195], v143 offset:39936
	global_load_lds_dwordx4 v[196:197], off
	v_lshl_add_u64 v[196:197], s[30:31], 0, v[132:133]
	s_mov_b32 m0, s52
	s_nop 0
	global_load_lds_dwordx4 v[196:197], off
	s_waitcnt lgkmcnt(8)
	s_barrier
	s_waitcnt lgkmcnt(0)
	s_waitcnt lgkmcnt(0)
	v_mfma_f32_16x16x32_bf16 v[124:127], v[144:147], v[160:163], v[124:127]
	v_mfma_f32_16x16x32_bf16 v[120:123], v[152:155], v[160:163], v[120:123]
	v_mfma_f32_16x16x32_bf16 v[116:119], v[144:147], v[168:171], v[116:119]
	v_mfma_f32_16x16x32_bf16 v[112:115], v[152:155], v[168:171], v[112:115]
	v_mfma_f32_16x16x32_bf16 v[108:111], v[144:147], v[180:183], v[108:111]
	v_mfma_f32_16x16x32_bf16 v[104:107], v[152:155], v[180:183], v[104:107]
	v_mfma_f32_16x16x32_bf16 v[100:103], v[144:147], v[188:191], v[100:103]
	v_mfma_f32_16x16x32_bf16 v[96:99], v[152:155], v[188:191], v[96:99]
	v_mfma_f32_16x16x32_bf16 v[124:127], v[148:151], v[164:167], v[124:127]
	v_mfma_f32_16x16x32_bf16 v[120:123], v[156:159], v[164:167], v[120:123]
	v_mfma_f32_16x16x32_bf16 v[116:119], v[148:151], v[172:175], v[116:119]
	v_mfma_f32_16x16x32_bf16 v[112:115], v[156:159], v[172:175], v[112:115]
	v_mfma_f32_16x16x32_bf16 v[108:111], v[148:151], v[184:187], v[108:111]
	v_mfma_f32_16x16x32_bf16 v[104:107], v[156:159], v[184:187], v[104:107]
	v_mfma_f32_16x16x32_bf16 v[100:103], v[148:151], v[192:195], v[100:103]
	v_mfma_f32_16x16x32_bf16 v[96:99], v[156:159], v[192:195], v[96:99]
	s_barrier
	s_add_i32 s30, 0, 0x1c000
	s_add_i32 s29, s29, s48
	v_add_u32_e32 v176, s30, v141
	v_lshl_add_u64 v[200:201], v[200:201], 0, s[40:41]
	s_mov_b32 m0, s29
	ds_read_b128 v[196:199], v176
	ds_read_b128 v[208:211], v176 offset:1024
	ds_read_b128 v[212:215], v176 offset:2048
	ds_read_b128 v[216:219], v176 offset:3072
	global_load_lds_dwordx4 v[200:201], off
	v_lshl_add_u64 v[200:201], v[220:221], 0, s[40:41]
	s_add_i32 m0, s29, 0x2000
	s_nop 0
	global_load_lds_dwordx4 v[200:201], off
	s_barrier
	s_waitcnt lgkmcnt(0)
	s_waitcnt lgkmcnt(0)
	v_mfma_f32_16x16x32_bf16 v[72:75], v[196:199], v[160:163], v[72:75]
	v_mfma_f32_16x16x32_bf16 v[64:67], v[212:215], v[160:163], v[64:67]
	v_mfma_f32_16x16x32_bf16 v[56:59], v[196:199], v[168:171], v[56:59]
	v_mfma_f32_16x16x32_bf16 v[48:51], v[212:215], v[168:171], v[48:51]
	v_mfma_f32_16x16x32_bf16 v[44:47], v[196:199], v[180:183], v[44:47]
	v_mfma_f32_16x16x32_bf16 v[40:43], v[212:215], v[180:183], v[40:43]
	v_mfma_f32_16x16x32_bf16 v[36:39], v[196:199], v[188:191], v[36:39]
	v_mfma_f32_16x16x32_bf16 v[32:35], v[212:215], v[188:191], v[32:35]
	v_mfma_f32_16x16x32_bf16 v[72:75], v[208:211], v[164:167], v[72:75]
	v_mfma_f32_16x16x32_bf16 v[64:67], v[216:219], v[164:167], v[64:67]
	v_mfma_f32_16x16x32_bf16 v[56:59], v[208:211], v[172:175], v[56:59]
	v_mfma_f32_16x16x32_bf16 v[48:51], v[216:219], v[172:175], v[48:51]
	v_mfma_f32_16x16x32_bf16 v[44:47], v[208:211], v[184:187], v[44:47]
	v_mfma_f32_16x16x32_bf16 v[40:43], v[216:219], v[184:187], v[40:43]
	v_mfma_f32_16x16x32_bf16 v[36:39], v[208:211], v[192:195], v[36:39]
	v_mfma_f32_16x16x32_bf16 v[32:35], v[216:219], v[192:195], v[32:35]
	s_mov_b32 m0, s56
	v_lshl_add_u64 v[200:201], v[222:223], 0, s[40:41]
	s_barrier
	ds_read_b128 v[160:163], v143 offset:49152
	ds_read_b128 v[164:167], v143 offset:50176
	ds_read_b128 v[168:171], v143 offset:51200
	ds_read_b128 v[172:175], v143 offset:52224
	ds_read_b128 v[180:183], v143 offset:53248
	ds_read_b128 v[184:187], v143 offset:54272
	ds_read_b128 v[188:191], v143 offset:55296
	ds_read_b128 v[192:195], v143 offset:56320
	global_load_lds_dwordx4 v[200:201], off
	v_lshl_add_u64 v[200:201], v[224:225], 0, s[40:41]
	s_mov_b32 m0, s57
	s_nop 0
	global_load_lds_dwordx4 v[200:201], off
	s_barrier
	s_waitcnt lgkmcnt(0)
	s_waitcnt lgkmcnt(0)
	v_mfma_f32_16x16x32_bf16 v[92:95], v[144:147], v[160:163], v[92:95]
	v_mfma_f32_16x16x32_bf16 v[88:91], v[152:155], v[160:163], v[88:91]
	v_mfma_f32_16x16x32_bf16 v[84:87], v[144:147], v[168:171], v[84:87]
	v_mfma_f32_16x16x32_bf16 v[80:83], v[152:155], v[168:171], v[80:83]
	v_mfma_f32_16x16x32_bf16 v[76:79], v[144:147], v[180:183], v[76:79]
	v_mfma_f32_16x16x32_bf16 v[68:71], v[152:155], v[180:183], v[68:71]
	v_mfma_f32_16x16x32_bf16 v[60:63], v[144:147], v[188:191], v[60:63]
	v_mfma_f32_16x16x32_bf16 v[52:55], v[152:155], v[188:191], v[52:55]
	v_mfma_f32_16x16x32_bf16 v[92:95], v[148:151], v[164:167], v[92:95]
	v_mfma_f32_16x16x32_bf16 v[88:91], v[156:159], v[164:167], v[88:91]
	v_mfma_f32_16x16x32_bf16 v[84:87], v[148:151], v[172:175], v[84:87]
	v_mfma_f32_16x16x32_bf16 v[80:83], v[156:159], v[172:175], v[80:83]
	v_mfma_f32_16x16x32_bf16 v[76:79], v[148:151], v[184:187], v[76:79]
	v_mfma_f32_16x16x32_bf16 v[68:71], v[156:159], v[184:187], v[68:71]
	v_mfma_f32_16x16x32_bf16 v[60:63], v[148:151], v[192:195], v[60:63]
	v_mfma_f32_16x16x32_bf16 v[52:55], v[156:159], v[192:195], v[52:55]
	s_barrier
	s_add_i32 s29, s30, s48
	v_lshl_add_u64 v[144:145], v[226:227], 0, s[40:41]
	s_mov_b32 m0, s29
	s_nop 0
	global_load_lds_dwordx4 v[144:145], off
	v_lshl_add_u64 v[144:145], v[228:229], 0, s[40:41]
	s_add_i32 m0, s29, 0x2000
	s_nop 0
	global_load_lds_dwordx4 v[144:145], off
	s_waitcnt vmcnt(6)
	s_barrier
	v_mfma_f32_16x16x32_bf16 v[28:31], v[196:199], v[160:163], v[28:31]
	v_mfma_f32_16x16x32_bf16 v[24:27], v[212:215], v[160:163], v[24:27]
	v_mfma_f32_16x16x32_bf16 v[20:23], v[196:199], v[168:171], v[20:23]
	v_mfma_f32_16x16x32_bf16 v[16:19], v[212:215], v[168:171], v[16:19]
	v_mfma_f32_16x16x32_bf16 v[12:15], v[196:199], v[180:183], v[12:15]
	v_mfma_f32_16x16x32_bf16 v[8:11], v[212:215], v[180:183], v[8:11]
	v_mfma_f32_16x16x32_bf16 v[4:7], v[196:199], v[188:191], v[4:7]
	v_mfma_f32_16x16x32_bf16 v[0:3], v[212:215], v[188:191], v[0:3]
	v_mfma_f32_16x16x32_bf16 v[28:31], v[208:211], v[164:167], v[28:31]
	v_mfma_f32_16x16x32_bf16 v[24:27], v[216:219], v[164:167], v[24:27]
	v_mfma_f32_16x16x32_bf16 v[20:23], v[208:211], v[172:175], v[20:23]
	v_mfma_f32_16x16x32_bf16 v[16:19], v[216:219], v[172:175], v[16:19]
	v_mfma_f32_16x16x32_bf16 v[12:15], v[208:211], v[184:187], v[12:15]
	v_mfma_f32_16x16x32_bf16 v[8:11], v[216:219], v[184:187], v[8:11]
	v_mfma_f32_16x16x32_bf16 v[4:7], v[208:211], v[192:195], v[4:7]
	v_mfma_f32_16x16x32_bf16 v[0:3], v[216:219], v[192:195], v[0:3]
	s_add_u32 s26, s26, 0x100
	s_addc_u32 s27, s27, 0
	s_add_u32 s13, s13, 0x100
	s_addc_u32 s15, s15, 0
	s_cmp_ge_u32 s60, s55
	s_mov_b32 s30, s60
	s_barrier
	s_cbranch_scc0 .LBB0_639
	s_lshl_b32 s13, s16, 8
	s_ashr_i32 s15, s16, 1
	s_and_b32 s13, s13, 0x100
	v_or_b32_e32 v145, s13, v142
	s_lshl_b32 s13, s15, s59
	s_add_i32 s26, s13, s54
	s_ashr_i32 s27, s26, 31
	s_lshl_b64 s[26:27], s[26:27], 12
	v_readlane_b32 s30, v255, 26
	v_lshl_add_u32 v144, s18, 8, v140
	v_readlane_b32 s31, v255, 27
	s_add_u32 s26, s30, s26
	s_addc_u32 s27, s31, s27
	v_lshlrev_b32_e32 v176, 1, v145
	v_pk_mul_f32 v[124:125], s[8:9], v[124:125]
	v_ashrrev_i32_e32 v145, 31, v144
	v_lshl_add_u64 v[146:147], s[26:27], 0, v[176:177]
	v_pk_mul_f32 v[148:149], s[10:11], v[122:123]
	v_pk_mul_f32 v[122:123], s[8:9], v[120:121]
	v_cvt_pk_bf16_f32 v120, v124, v125
	v_lshlrev_b64 v[124:125], 12, v[144:145]
	v_pk_mul_f32 v[126:127], s[10:11], v[126:127]
	v_lshl_add_u64 v[124:125], v[146:147], 0, v[124:125]
	v_cvt_pk_bf16_f32 v121, v126, v127
	v_pk_mul_f32 v[116:117], s[8:9], v[116:117]
	v_cvt_pk_bf16_f32 v122, v122, v123
	v_cvt_pk_bf16_f32 v123, v148, v149
	global_store_dwordx4 v[124:125], v[120:123], off offset:3072
	v_pk_mul_f32 v[118:119], s[10:11], v[118:119]
	v_pk_mul_f32 v[108:109], s[8:9], v[108:109]
	v_pk_mul_f32 v[120:121], s[10:11], v[114:115]
	v_pk_mul_f32 v[114:115], s[8:9], v[112:113]
	v_cvt_pk_bf16_f32 v112, v116, v117
	v_or_b32_e32 v116, 16, v144
	v_ashrrev_i32_e32 v117, 31, v116
	v_lshlrev_b64 v[116:117], 12, v[116:117]
	v_cvt_pk_bf16_f32 v113, v118, v119
	v_lshl_add_u64 v[116:117], v[146:147], 0, v[116:117]
	v_cvt_pk_bf16_f32 v114, v114, v115
	v_cvt_pk_bf16_f32 v115, v120, v121
	global_store_dwordx4 v[116:117], v[112:115], off offset:3072
	v_pk_mul_f32 v[110:111], s[10:11], v[110:111]
	v_pk_mul_f32 v[100:101], s[8:9], v[100:101]
	v_pk_mul_f32 v[112:113], s[10:11], v[106:107]
	v_pk_mul_f32 v[106:107], s[8:9], v[104:105]
	v_cvt_pk_bf16_f32 v104, v108, v109
	v_or_b32_e32 v108, 32, v144
	v_ashrrev_i32_e32 v109, 31, v108
	v_lshlrev_b64 v[108:109], 12, v[108:109]
	v_cvt_pk_bf16_f32 v105, v110, v111
	v_lshl_add_u64 v[108:109], v[146:147], 0, v[108:109]
	v_cvt_pk_bf16_f32 v106, v106, v107
	v_cvt_pk_bf16_f32 v107, v112, v113
	global_store_dwordx4 v[108:109], v[104:107], off offset:3072
	v_pk_mul_f32 v[102:103], s[10:11], v[102:103]
	v_pk_mul_f32 v[92:93], s[8:9], v[92:93]
	v_pk_mul_f32 v[104:105], s[10:11], v[98:99]
	v_pk_mul_f32 v[98:99], s[8:9], v[96:97]
	v_cvt_pk_bf16_f32 v96, v100, v101
	v_or_b32_e32 v100, 48, v144
	v_ashrrev_i32_e32 v101, 31, v100
	v_lshlrev_b64 v[100:101], 12, v[100:101]
	v_cvt_pk_bf16_f32 v97, v102, v103
	v_lshl_add_u64 v[100:101], v[146:147], 0, v[100:101]
	s_mov_b64 s[26:27], 0x80000
	v_cvt_pk_bf16_f32 v98, v98, v99
	v_cvt_pk_bf16_f32 v99, v104, v105
	global_store_dwordx4 v[100:101], v[96:99], off offset:3072
	v_pk_mul_f32 v[94:95], s[10:11], v[94:95]
	v_pk_mul_f32 v[84:85], s[8:9], v[84:85]
	v_pk_mul_f32 v[96:97], s[10:11], v[90:91]
	v_pk_mul_f32 v[90:91], s[8:9], v[88:89]
	v_cvt_pk_bf16_f32 v88, v92, v93
	v_cvt_pk_bf16_f32 v89, v94, v95
	v_lshl_add_u64 v[92:93], v[124:125], 0, s[26:27]
	s_mov_b64 s[26:27], 0x90000
	v_cvt_pk_bf16_f32 v90, v90, v91
	v_cvt_pk_bf16_f32 v91, v96, v97
	global_store_dwordx4 v[92:93], v[88:91], off offset:3072
	v_pk_mul_f32 v[86:87], s[10:11], v[86:87]
	v_pk_mul_f32 v[76:77], s[8:9], v[76:77]
	v_pk_mul_f32 v[88:89], s[10:11], v[82:83]
	v_pk_mul_f32 v[82:83], s[8:9], v[80:81]
	v_cvt_pk_bf16_f32 v80, v84, v85
	v_cvt_pk_bf16_f32 v81, v86, v87
	v_lshl_add_u64 v[84:85], v[124:125], 0, s[26:27]
	s_mov_b64 s[26:27], 0xa0000
	v_cvt_pk_bf16_f32 v82, v82, v83
	v_cvt_pk_bf16_f32 v83, v88, v89
	global_store_dwordx4 v[84:85], v[80:83], off offset:3072
	v_pk_mul_f32 v[78:79], s[10:11], v[78:79]
	v_pk_mul_f32 v[60:61], s[8:9], v[60:61]
	v_pk_mul_f32 v[80:81], s[10:11], v[70:71]
	v_pk_mul_f32 v[70:71], s[8:9], v[68:69]
	v_cvt_pk_bf16_f32 v68, v76, v77
	v_cvt_pk_bf16_f32 v69, v78, v79
	v_lshl_add_u64 v[76:77], v[124:125], 0, s[26:27]
	v_cvt_pk_bf16_f32 v70, v70, v71
	v_cvt_pk_bf16_f32 v71, v80, v81
	global_store_dwordx4 v[76:77], v[68:71], off offset:3072
	s_mov_b64 s[26:27], 0xb0000
	v_pk_mul_f32 v[62:63], s[10:11], v[62:63]
	v_pk_mul_f32 v[68:69], s[10:11], v[54:55]
	v_pk_mul_f32 v[54:55], s[8:9], v[52:53]
	v_cvt_pk_bf16_f32 v52, v60, v61
	v_cvt_pk_bf16_f32 v53, v62, v63
	v_lshl_add_u64 v[60:61], v[124:125], 0, s[26:27]
	v_cvt_pk_bf16_f32 v54, v54, v55
	v_cvt_pk_bf16_f32 v55, v68, v69
	global_store_dwordx4 v[60:61], v[52:55], off offset:3072
	v_pk_mul_f32 v[62:63], s[10:11], v[66:67]
	v_pk_mul_f32 v[64:65], s[8:9], v[64:65]
	v_pk_mul_f32 v[54:55], s[10:11], v[74:75]
	v_pk_mul_f32 v[52:53], s[8:9], v[72:73]
	v_pk_mul_f32 v[46:47], s[10:11], v[46:47]
	v_cvt_pk_bf16_f32 v52, v52, v53
	v_cvt_pk_bf16_f32 v53, v54, v55
	v_cvt_pk_bf16_f32 v54, v64, v65
	v_cvt_pk_bf16_f32 v55, v62, v63
	global_store_dwordx4 v[124:125], v[52:55], off offset:3328
	v_pk_mul_f32 v[44:45], s[8:9], v[44:45]
	v_pk_mul_f32 v[38:39], s[10:11], v[38:39]
	v_pk_mul_f32 v[52:53], s[10:11], v[58:59]
	v_pk_mul_f32 v[54:55], s[8:9], v[56:57]
	v_pk_mul_f32 v[56:57], s[10:11], v[50:51]
	v_pk_mul_f32 v[50:51], s[8:9], v[48:49]
	v_cvt_pk_bf16_f32 v48, v54, v55
	v_cvt_pk_bf16_f32 v49, v52, v53
	v_pk_mul_f32 v[36:37], s[8:9], v[36:37]
	v_cvt_pk_bf16_f32 v50, v50, v51
	v_cvt_pk_bf16_f32 v51, v56, v57
	global_store_dwordx4 v[116:117], v[48:51], off offset:3328
	v_pk_mul_f32 v[30:31], s[10:11], v[30:31]
	v_pk_mul_f32 v[28:29], s[8:9], v[28:29]
	v_pk_mul_f32 v[48:49], s[10:11], v[42:43]
	v_pk_mul_f32 v[42:43], s[8:9], v[40:41]
	v_cvt_pk_bf16_f32 v40, v44, v45
	v_cvt_pk_bf16_f32 v41, v46, v47
	v_pk_mul_f32 v[22:23], s[10:11], v[22:23]
	v_cvt_pk_bf16_f32 v42, v42, v43
	v_cvt_pk_bf16_f32 v43, v48, v49
	global_store_dwordx4 v[108:109], v[40:43], off offset:3328
	v_pk_mul_f32 v[20:21], s[8:9], v[20:21]
	v_pk_mul_f32 v[14:15], s[10:11], v[14:15]
	v_pk_mul_f32 v[40:41], s[10:11], v[34:35]
	v_pk_mul_f32 v[34:35], s[8:9], v[32:33]
	v_cvt_pk_bf16_f32 v32, v36, v37
	v_cvt_pk_bf16_f32 v33, v38, v39
	v_pk_mul_f32 v[12:13], s[8:9], v[12:13]
	v_cvt_pk_bf16_f32 v34, v34, v35
	v_cvt_pk_bf16_f32 v35, v40, v41
	global_store_dwordx4 v[100:101], v[32:35], off offset:3328
	s_and_b64 vcc, exec, s[6:7]
	s_mov_b32 s16, s12
	v_pk_mul_f32 v[32:33], s[10:11], v[26:27]
	v_pk_mul_f32 v[26:27], s[8:9], v[24:25]
	v_cvt_pk_bf16_f32 v24, v28, v29
	v_cvt_pk_bf16_f32 v25, v30, v31
	s_mov_b32 s18, s14
	v_cvt_pk_bf16_f32 v26, v26, v27
	v_cvt_pk_bf16_f32 v27, v32, v33
	global_store_dwordx4 v[92:93], v[24:27], off offset:3328
	s_mov_b64 s[30:31], s[24:25]
	s_mov_b64 s[26:27], s[20:21]
	v_pk_mul_f32 v[24:25], s[10:11], v[18:19]
	v_pk_mul_f32 v[18:19], s[8:9], v[16:17]
	v_cvt_pk_bf16_f32 v16, v20, v21
	v_cvt_pk_bf16_f32 v17, v22, v23
	v_pk_mul_f32 v[6:7], s[10:11], v[6:7]
	v_cvt_pk_bf16_f32 v18, v18, v19
	v_cvt_pk_bf16_f32 v19, v24, v25
	global_store_dwordx4 v[84:85], v[16:19], off offset:3328
	v_pk_mul_f32 v[4:5], s[8:9], v[4:5]
	s_nop 0
	v_pk_mul_f32 v[16:17], s[10:11], v[10:11]
	v_pk_mul_f32 v[10:11], s[8:9], v[8:9]
	v_cvt_pk_bf16_f32 v8, v12, v13
	v_cvt_pk_bf16_f32 v9, v14, v15
	s_nop 0
	v_cvt_pk_bf16_f32 v10, v10, v11
	v_cvt_pk_bf16_f32 v11, v16, v17
	global_store_dwordx4 v[76:77], v[8:11], off offset:3328
	s_nop 1
	v_pk_mul_f32 v[8:9], s[10:11], v[2:3]
	v_pk_mul_f32 v[2:3], s[8:9], v[0:1]
	v_cvt_pk_bf16_f32 v0, v4, v5
	v_cvt_pk_bf16_f32 v1, v6, v7
	s_nop 0
	v_cvt_pk_bf16_f32 v2, v2, v3
	v_cvt_pk_bf16_f32 v3, v8, v9
	global_store_dwordx4 v[60:61], v[0:3], off offset:3328
	s_cbranch_vccz .LBB0_636
	s_waitcnt vmcnt(0)
	s_setprio 0
	s_cmpk_gt_u32 s1, 0xff
	s_cbranch_scc1 .LBB0_626
	s_barrier
	s_branch .LBB0_626

.LBB0_647:
	s_andn2_b64 vcc, exec, s[4:5]
	s_cbranch_vccnz .LBB0_709
	v_ashrrev_i32_e32 v1, 31, v12
	v_lshrrev_b32_e32 v1, 26, v1
	v_add_u32_e32 v1, v12, v1
	v_ashrrev_i32_e32 v8, 6, v1
	v_bfe_i32 v1, v12, 27, 1
	v_lshlrev_b32_e32 v0, 4, v12
	v_lshrrev_b32_e32 v1, 22, v1
	v_add_u32_e32 v1, v0, v1
	v_and_b32_e32 v1, 0xfffffc00, v1
	v_readlane_b32 s4, v255, 32
	v_sub_u32_e32 v1, v0, v1
	v_readlane_b32 s5, v255, 33
	v_lshrrev_b32_e32 v2, 4, v1
	s_and_b64 s[4:5], s[4:5], exec
	v_bitop3_b32 v2, v2, v1, 32 bitop3:0x6c
	v_ashrrev_i32_e32 v1, 31, v1
	v_readlane_b32 s4, v255, 40
	v_lshrrev_b32_e32 v1, 26, v1
	v_readlane_b32 s5, v255, 41
	v_add_u32_e32 v1, v2, v1
	s_load_dwordx2 s[4:5], s[4:5], 0xe0
	v_ashrrev_i32_e32 v9, 6, v1
	v_lshlrev_b32_e32 v3, 3, v8
	v_mul_i32_i24_e32 v4, 64, v9
	v_and_b32_e32 v3, -16, v3
	v_sub_u32_e32 v2, v2, v4
	v_mov_b32_e32 v6, 1
	s_mov_b32 s3, 0xa34000
	v_add_u32_e32 v1, v9, v3
	v_lshlrev_b32_e32 v3, 5, v8
	v_ashrrev_i16_sdwa v2, v6, sext(v2) dst_sel:DWORD dst_unused:UNUSED_PAD src0_sel:DWORD src1_sel:BYTE_0
	s_cselect_b32 s3, s3, 0x7a34000
	v_and_b32_e32 v3, 32, v3
	v_bfe_i32 v10, v2, 0, 16
	s_waitcnt lgkmcnt(0)
	s_add_u32 s26, s4, s3
	v_and_b32_e32 v5, 3, v9
	s_mov_b32 s4, 0xfffe0
	v_add_lshl_u32 v3, v3, v10, 1
	v_add_u32_e32 v0, 0x2000, v0
	v_lshlrev_b32_e32 v2, 1, v1
	v_lshrrev_b32_e32 v4, 2, v1
	v_and_or_b32 v5, v1, s4, v5
	v_lshl_add_u32 v128, v1, 12, v3
	v_ashrrev_i32_e32 v1, 31, v0
	v_lshrrev_b32_e32 v1, 22, v1
	v_add_u32_e32 v1, v0, v1
	v_ashrrev_i32_e32 v11, 10, v1
	v_mul_i32_i24_e32 v1, 0x400, v11
	v_sub_u32_e32 v0, v0, v1
	v_and_b32_e32 v2, 24, v2
	v_and_b32_e32 v4, 4, v4
	v_lshrrev_b32_e32 v1, 4, v0
	v_or3_b32 v2, v5, v4, v2
	v_bitop3_b32 v0, v1, v0, 32 bitop3:0x6c
	v_lshl_add_u32 v130, v2, 12, v3
	v_ashrrev_i32_e32 v2, 31, v0
	v_lshrrev_b32_e32 v2, 26, v2
	v_lshlrev_b32_e32 v1, 3, v11
	v_add_u32_e32 v2, v0, v2
	v_and_b32_e32 v1, -16, v1
	v_ashrrev_i32_e32 v13, 6, v2
	v_add_u32_e32 v1, v13, v1
	v_and_b32_e32 v4, 3, v13
	s_addc_u32 s27, s5, 0
	v_and_b32_e32 v2, 0xc0, v2
	v_and_or_b32 v4, v1, s4, v4
	s_ashr_i32 s4, s1, 6
	s_ashr_i32 s17, s16, 31
	s_ashr_i32 s15, s14, 31
	s_ashr_i32 s3, s1, 8
	v_sub_u32_e32 v0, v0, v2
	s_lshl_b32 s28, s4, 10
	s_lshl_b64 s[6:7], s[16:17], 20
	s_lshl_b64 s[8:9], s[14:15], 20
	v_ashrrev_i16_sdwa v0, v6, sext(v0) dst_sel:DWORD dst_unused:UNUSED_PAD src0_sel:DWORD src1_sel:BYTE_0
	s_add_u32 s18, s26, s8
	v_lshlrev_b32_e32 v3, 5, v11
	v_bfe_i32 v14, v0, 0, 16
	v_lshlrev_b32_e32 v0, 1, v1
	v_lshrrev_b32_e32 v2, 2, v1
	s_addc_u32 s19, s27, s9
	s_add_i32 s30, s28, 0
	v_and_b32_e32 v3, 32, v3
	v_and_b32_e32 v0, 24, v0
	v_and_b32_e32 v2, 4, v2
	s_add_i32 m0, s30, 0x10000
	v_or3_b32 v0, v4, v2, v0
	v_add_lshl_u32 v2, v3, v14, 1
	global_load_lds_dwordx4 v130, s[18:19]
	s_add_i32 m0, s30, 0x12000
	v_readlane_b32 s8, v255, 26
	v_lshl_add_u32 v134, v0, 12, v2
	v_readlane_b32 s9, v255, 27
	s_add_u32 s20, s8, s6
	global_load_lds_dwordx4 v134, s[18:19]
	s_addc_u32 s21, s9, s7
	s_mov_b32 m0, s30
	s_add_i32 s31, s30, 0x2000
	v_lshl_add_u32 v132, v1, 12, v2
	global_load_lds_dwordx4 v128, s[20:21]
	s_mov_b32 m0, s31
	s_add_u32 s6, s18, 0x80000
	global_load_lds_dwordx4 v132, s[20:21]
	s_addc_u32 s7, s19, 0
	s_add_i32 m0, s30, 0x14000
	v_mov_b32_e32 v131, v177
	global_load_lds_dwordx4 v130, s[6:7]
	s_add_i32 m0, s30, 0x16000
	v_mov_b32_e32 v135, v177
	global_load_lds_dwordx4 v134, s[6:7]
	s_add_u32 s6, s20, 0x80000
	s_addc_u32 s7, s21, 0
	s_add_i32 s33, s30, 0x4000
	s_mov_b32 m0, s33
	s_add_i32 s37, s30, 0x6000
	global_load_lds_dwordx4 v128, s[6:7]
	s_mov_b32 m0, s37
	v_mov_b32_e32 v129, v177
	global_load_lds_dwordx4 v132, s[6:7]
	v_mov_b32_e32 v133, v177
	v_lshl_add_u64 v[6:7], s[18:19], 0, v[130:131]
	v_lshl_add_u64 v[4:5], s[18:19], 0, v[134:135]
	v_lshl_add_u64 v[2:3], s[20:21], 0, v[128:129]
	s_cmp_lg_u32 s3, 1
	v_lshl_add_u64 v[0:1], s[20:21], 0, v[132:133]
	s_cbranch_scc1 .LBB0_650
	s_barrier
	s_setprio 1

.LBB0_706:
	s_waitcnt vmcnt(0)
	s_setprio 0
	s_cmpk_gt_u32 s1, 0xff
	s_cbranch_scc1 .LBB0_708
	s_barrier
